# mixer phase start: attention Q loads issued behind the bias-table loads (two cold round trips overlapped)
# speedup vs baseline: 1.0036x; 1.0036x over previous
.LBB0_333:
	s_andn2_b64 vcc, exec, s[24:25]
	s_cbranch_vccnz .LBB0_407
	v_mov_b32_e32 v34, v244
	v_readlane_b32 s24, v254, 58
	v_readlane_b32 s50, v255, 40
	v_readlane_b32 s51, v255, 41
	s_nop 3
	s_mul_i32 s26, s24, 0x744
	s_add_u32 s50, s50, s26
	s_addc_u32 s51, s51, 0
	s_mul_i32 s0, s24, 0xa00
	s_add_i32 s26, s0, 0x100
	v_lshlrev_b32_e32 v100, 2, v34
	s_waitcnt vmcnt(0)
	global_load_dword v101, v100, s[50:51]
	global_load_dword v102, v100, s[50:51] offset:256
	global_load_dword v103, v100, s[50:51] offset:512
	global_load_dword v104, v100, s[50:51] offset:768
	global_load_dword v105, v100, s[50:51] offset:1024
	global_load_dword v106, v100, s[50:51] offset:1280
	global_load_dword v107, v100, s[50:51] offset:1536
	v_cmp_gt_u32_e32 vcc, 17, v34
	s_and_saveexec_b64 s[24:25], vcc
	global_load_dword v108, v100, s[50:51] offset:1792
	s_or_b64 exec, exec, s[24:25]
	v_add_u32_e32 v109, s26, v100
	v_readlane_b32 s34, v254, 58
	v_readlane_b32 s35, v254, 59
	s_ashr_i32 s35, s34, 31
	v_lshlrev_b32_e32 v0, 3, v34
	s_lshl_b64 s[24:25], s[34:35], 11
	v_readlane_b32 s26, v252, 9
	s_add_u32 s26, s26, s24
	v_readlane_b32 s27, v252, 10
	v_ashrrev_i32_e32 v1, 31, v0
	s_addc_u32 s27, s27, s25
	v_lshlrev_b64 v[162:163], 1, v[0:1]
	v_lshl_add_u64 v[24:25], s[26:27], 0, v[162:163]
	v_readlane_b32 s26, v252, 33
	v_readlane_b32 s27, v252, 34
	s_waitcnt lgkmcnt(0)
	v_and_b32_e32 v161, 15, v34
	v_ashrrev_i32_e32 v32, 2, v34
	v_lshl_add_u64 v[4:5], v[24:25], 0, s[26:27]
	v_readlane_b32 s26, v252, 29
	v_readlane_b32 s27, v252, 30
	global_load_dwordx4 v[0:3], v[4:5], off
	s_nop 0
	global_load_dwordx4 v[4:7], v[4:5], off offset:1024
	v_lshl_add_u64 v[12:13], v[24:25], 0, s[26:27]
	v_readlane_b32 s26, v252, 31
	v_readlane_b32 s27, v252, 32
	global_load_dwordx4 v[8:11], v[12:13], off
	s_nop 0
	global_load_dwordx4 v[12:15], v[12:13], off offset:1024
	v_lshl_add_u64 v[20:21], v[24:25], 0, s[26:27]
	v_readlane_b32 s26, v252, 36
	v_readlane_b32 s27, v252, 37
	global_load_dwordx4 v[16:19], v[20:21], off
	s_nop 0
	global_load_dwordx4 v[20:23], v[20:21], off offset:1024
	v_lshl_add_u64 v[28:29], v[24:25], 0, s[26:27]
	global_load_dwordx4 v[24:27], v[28:29], off
	s_nop 0
	global_load_dwordx4 v[28:31], v[28:29], off offset:1024
	s_waitcnt vmcnt(8)
	v_mul_f32_e32 v101, 0x3fb8aa3b, v101
	v_mul_f32_e32 v102, 0x3fb8aa3b, v102
	v_mul_f32_e32 v103, 0x3fb8aa3b, v103
	v_mul_f32_e32 v104, 0x3fb8aa3b, v104
	v_mul_f32_e32 v105, 0x3fb8aa3b, v105
	v_mul_f32_e32 v106, 0x3fb8aa3b, v106
	v_mul_f32_e32 v107, 0x3fb8aa3b, v107
	v_mul_f32_e32 v108, 0x3fb8aa3b, v108
	ds_write_b32 v109, v101
	ds_write_b32 v109, v102 offset:256
	ds_write_b32 v109, v103 offset:512
	ds_write_b32 v109, v104 offset:768
	ds_write_b32 v109, v105 offset:1024
	ds_write_b32 v109, v106 offset:1280
	ds_write_b32 v109, v107 offset:1536
	v_cmp_gt_u32_e32 vcc, 17, v34
	s_and_saveexec_b64 s[98:99], vcc
	ds_write_b32 v109, v108 offset:1792
	s_or_b64 exec, exec, s[98:99]
	s_waitcnt lgkmcnt(0)
.LBB0_347:
	v_and_b32_e32 v160, -4, v32
	v_sub_u32_e64 v32, v161, 8 clamp
	v_sub_u32_e32 v32, v160, v32
	v_add_u32_e32 v44, 33, v32
	v_add_u32_e32 v37, 1, v32
	v_add_u32_e32 v45, 34, v32
	v_cmp_gt_u32_e32 vcc, 16, v44
	v_sub_u32_e32 v35, v160, v161
	v_add_u32_e32 v38, 2, v32
	v_add_u32_e32 v46, 35, v32
	v_cmp_gt_u32_e64 s[46:47], 16, v37
	v_cndmask_b32_e32 v37, 0, v231, vcc
	v_cmp_gt_u32_e32 vcc, 16, v45
	v_add_u32_e32 v39, 3, v32
	v_and_b32_e32 v43, -16, v32
	v_add_u32_e32 v49, -8, v35
	v_cmp_gt_u32_e64 s[48:49], 16, v38
	v_cndmask_b32_e32 v38, 0, v232, vcc
	v_cmp_gt_u32_e32 vcc, 16, v46
	s_movk_i32 s30, 0xffd0
	v_add_u32_e32 v40, 17, v32
	v_add_u32_e32 v47, 49, v32
	v_cmp_gt_u32_e64 s[50:51], 16, v39
	v_cndmask_b32_e32 v39, 0, v233, vcc
	v_cmp_eq_u32_e32 vcc, s30, v43
	v_and_b32_e32 v46, -16, v49
	s_movk_i32 s26, 0xffe0
	v_lshl_add_u32 v168, v34, 4, s55
	s_movk_i32 s27, 0xffef
	v_add_u32_e32 v41, 18, v32
	v_add_u32_e32 v48, 50, v32
	v_cmp_gt_u32_e64 s[52:53], 16, v40
	v_cndmask_b32_e32 v40, 0, v234, vcc
	v_cmp_gt_u32_e32 vcc, 16, v47
	v_cmp_eq_u32_e64 s[58:59], s26, v46
	v_cmp_gt_u32_e64 s[42:43], 16, v32
	v_cmp_lt_u32_e64 s[44:45], s27, v32
	v_add_u32_e32 v42, 19, v32
	v_add_u32_e32 v32, 51, v32
	v_cmp_gt_u32_e64 s[54:55], 16, v41
	v_cndmask_b32_e32 v41, 0, v235, vcc
	v_cmp_gt_u32_e32 vcc, 16, v48
	v_add_u32_e32 v50, 43, v35
	v_cmp_gt_u32_e64 s[56:57], 16, v42
	v_cndmask_b32_e32 v42, 0, v236, vcc
	v_cmp_gt_u32_e32 vcc, 16, v32
	v_add_u32_e32 v51, 42, v35
	v_add_u32_e32 v52, 41, v35
	v_cndmask_b32_e32 v32, 0, v237, vcc
	v_cmp_gt_u32_e32 vcc, 16, v50
	v_add_u32_e32 v53, 27, v35
	v_readlane_b32 s31, v252, 41
	v_cndmask_b32_e32 v43, 0, v237, vcc
	v_cmp_gt_u32_e32 vcc, 16, v51
	v_mov_b32_e32 v169, 0xf149f2ca
	v_mov_b32_e32 v171, 0xf149f2ca
	v_cndmask_b32_e32 v44, 0, v236, vcc
	v_cmp_gt_u32_e32 vcc, 16, v52
	v_mov_b32_e32 v172, 0xf149f2ca
	v_mov_b32_e32 v170, 0xf149f2ca
	v_cndmask_b32_e32 v45, 0, v235, vcc
	v_cmp_eq_u32_e32 vcc, s30, v46
	v_readlane_b32 s60, v252, 47
	s_waitcnt vmcnt(7)
	ds_write_b128 v168, v[0:3] offset:20480
	s_waitcnt vmcnt(6)
	ds_write_b128 v168, v[4:7] offset:21504
	s_waitcnt vmcnt(5)
	ds_write_b128 v168, v[8:11] offset:22528
	s_waitcnt vmcnt(4)
	ds_write_b128 v168, v[12:15] offset:23552
	s_waitcnt vmcnt(3)
	ds_write_b128 v168, v[16:19] offset:24576
	s_waitcnt vmcnt(2)
	ds_write_b128 v168, v[20:23] offset:25600
	s_waitcnt vmcnt(1)
	ds_write_b128 v168, v[24:27] offset:26624
	s_waitcnt vmcnt(0)
	ds_write_b128 v168, v[28:31] offset:27648
	v_cndmask_b32_e64 v3, 0, v238, s[58:59]
	v_cmp_lt_u32_e64 s[58:59], s27, v49
	v_add_u32_e32 v9, -6, v35
	v_add_u32_e32 v10, -7, v35
	v_cndmask_b32_e64 v7, 0, 16, s[58:59]
	v_cmp_gt_u32_e64 s[58:59], 16, v49
	v_add_u32_e32 v6, 9, v35
	v_add_u32_e32 v8, -5, v35
	v_cmp_gt_u32_e64 s[74:75], 16, v9
	v_cmp_gt_u32_e64 s[76:77], 16, v10
	v_cndmask_b32_e64 v11, 0, 1, s[58:59]
	v_add_u32_e32 v4, 11, v35
	v_add_u32_e32 v5, 10, v35
	v_cmp_gt_u32_e64 s[70:71], 16, v6
	v_cmp_gt_u32_e64 s[72:73], 16, v8
	v_cndmask_b32_e64 v9, 0, 4, s[74:75]
	v_cndmask_b32_e64 v10, 0, 2, s[76:77]
	v_or_b32_e32 v7, v7, v11
	v_add_u32_e32 v1, 26, v35
	v_add_u32_e32 v2, 25, v35
	v_cmp_gt_u32_e64 s[66:67], 16, v4
	v_cmp_gt_u32_e64 s[68:69], 16, v5
	v_cndmask_b32_e64 v6, 0, 32, s[70:71]
	v_cndmask_b32_e64 v8, 0, 8, s[72:73]
	v_or3_b32 v7, v7, v10, v9
	v_cmp_gt_u32_e64 s[62:63], 16, v1
	v_cmp_gt_u32_e64 s[64:65], 16, v2
	v_cndmask_b32_e64 v4, 0, v239, s[66:67]
	v_cndmask_b32_e64 v5, 0, 64, s[68:69]
	v_or3_b32 v6, v7, v8, v6
	v_cndmask_b32_e32 v47, 0, v234, vcc
	v_cmp_gt_u32_e32 vcc, 16, v53
	v_cndmask_b32_e64 v1, 0, v232, s[62:63]
	v_cndmask_b32_e64 v2, 0, v231, s[64:65]
	v_or3_b32 v4, v6, v5, v4
	v_cndmask_b32_e32 v0, 0, v233, vcc
	v_or3_b32 v1, v4, v2, v1
	v_or3_b32 v0, v1, v0, v45
	v_or3_b32 v1, v41, v42, v40
	v_or3_b32 v0, v0, v44, v43
	v_or3_b32 v1, v1, v39, v38
	v_or3_b32 v0, v0, v3, v47
	v_or3_b32 v1, v1, v37, v32
	v_lshl_add_u32 v32, v0, 16, v1
	v_subrev_u32_e32 v1, 23, v35
	v_cmp_gt_u32_e64 s[78:79], 16, v1
	v_subrev_u32_e32 v1, 22, v35
	v_subrev_u32_e32 v0, 24, v35
	v_cndmask_b32_e64 v37, 0, 2, s[78:79]
	v_cmp_gt_u32_e64 s[78:79], 16, v1
	v_subrev_u32_e32 v1, 21, v35
	v_cmp_gt_u32_e64 s[58:59], 16, v0
	v_cndmask_b32_e64 v38, 0, 4, s[78:79]
	v_cmp_gt_u32_e64 s[78:79], 16, v1
	v_cndmask_b32_e64 v42, 0, v239, s[72:73]
	v_cndmask_b32_e64 v40, 0, 32, s[76:77]
	v_cndmask_b32_e64 v35, 0, 8, s[78:79]
	v_cmp_lt_u32_e64 s[78:79], s27, v0
	v_and_b32_e32 v0, -16, v0
	v_cmp_eq_u32_e64 s[72:73], s26, v0
	v_cndmask_b32_e64 v41, 0, 64, s[74:75]
	v_cndmask_b32_e64 v39, 0, 16, s[78:79]
	v_cndmask_b32_e64 v43, 0, v238, s[72:73]
	v_or_b32_e32 v1, v42, v43
	v_or3_b32 v1, v1, v40, v41
	v_or3_b32 v1, v1, v39, v38
	v_or3_b32 v1, v1, v37, v35
	v_cndmask_b32_e64 v2, 0, v231, s[70:71]
	v_cndmask_b32_e64 v3, 0, v232, s[68:69]
	v_or3_b32 v44, v2, v3, v1
	v_cndmask_b32_e64 v1, 0, v233, s[66:67]
	v_cmp_eq_u32_e64 s[66:67], s30, v0
	v_bfrev_b32_e32 v7, 8
	s_waitcnt lgkmcnt(0)
	s_movk_i32 s72, 0x4000
	v_cndmask_b32_e64 v0, 0, v234, s[66:67]
	v_or3_b32 v45, v0, v1, v44
	v_cndmask_b32_e64 v0, 0, v235, s[64:65]
	v_cndmask_b32_e64 v1, 0, v236, s[62:63]
	v_or3_b32 v46, v0, v1, v45
	v_min_u32_e32 v1, 8, v161
	v_sub_u32_e32 v1, v160, v1
	v_add_u32_e32 v3, 11, v1
	v_cndmask_b32_e32 v0, 0, v237, vcc
	v_cmp_gt_u32_e32 vcc, 16, v3
	v_bfrev_b32_e32 v3, 1
	v_add_u32_e32 v4, 10, v1
	v_subrev_u32_e32 v2, 40, v1
	v_cndmask_b32_e32 v3, 0, v3, vcc
	v_cmp_gt_u32_e32 vcc, 16, v4
	v_add_u32_e32 v5, 9, v1
	v_and_b32_e32 v6, -16, v2
	v_cndmask_b32_e64 v4, 0, 2.0, vcc
	v_cmp_gt_u32_e32 vcc, 16, v5
	v_bfrev_b32_e32 v5, 4
	v_add_u32_e32 v8, -5, v1
	v_cndmask_b32_e32 v5, 0, v5, vcc
	v_cmp_eq_u32_e32 vcc, s30, v6
	v_add_u32_e32 v9, -6, v1
	v_add_u32_e32 v10, -7, v1
	v_cndmask_b32_e32 v7, 0, v7, vcc
	v_cmp_gt_u32_e32 vcc, 16, v8
	v_bfrev_b32_e32 v8, 16
	v_subrev_u32_e32 v11, 21, v1
	v_cndmask_b32_e32 v8, 0, v8, vcc
	v_cmp_gt_u32_e32 vcc, 16, v9
	v_bfrev_b32_e32 v9, 32
	v_subrev_u32_e32 v12, 22, v1
	v_cndmask_b32_e32 v9, 0, v9, vcc
	v_cmp_gt_u32_e32 vcc, 16, v10
	v_bfrev_b32_e32 v10, 64
	v_subrev_u32_e32 v13, 23, v1
	v_cndmask_b32_e32 v10, 0, v10, vcc
	v_cmp_eq_u32_e32 vcc, s26, v6
	v_subrev_u32_e32 v14, 37, v1
	v_subrev_u32_e32 v15, 38, v1
	v_cndmask_b32_e32 v6, 0, v245, vcc
	v_cmp_gt_u32_e32 vcc, 16, v11
	v_mov_b32_e32 v11, 0x800000
	v_subrev_u32_e32 v1, 39, v1
	v_cndmask_b32_e32 v11, 0, v11, vcc
	v_cmp_gt_u32_e32 vcc, 16, v12
	v_mov_b32_e32 v12, 0x400000
	v_readlane_b32 s26, v252, 38
	v_cndmask_b32_e32 v12, 0, v12, vcc
	v_cmp_gt_u32_e32 vcc, 16, v13
	v_mov_b32_e32 v13, 0x200000
	s_add_u32 s26, s26, s24
	v_cndmask_b32_e32 v13, 0, v13, vcc
	v_cmp_lt_u32_e32 vcc, s27, v2
	v_readlane_b32 s27, v252, 39
	s_addc_u32 s27, s27, s25
	v_cndmask_b32_e32 v2, 0, v250, vcc
	v_cmp_gt_u32_e32 vcc, 16, v14
	v_readlane_b32 s30, v252, 40
	v_bfe_i32 v156, v32, 16, 1
	v_cndmask_b32_e32 v14, 0, v251, vcc
	v_cmp_gt_u32_e32 vcc, 16, v15
	v_bfe_i32 v157, v32, 17, 1
	v_bfe_i32 v158, v32, 18, 1
	v_cndmask_b32_e32 v15, 0, v240, vcc
	v_cmp_gt_u32_e32 vcc, 16, v1
	v_bfe_i32 v159, v32, 19, 1
	v_bfe_i32 v173, v32, 20, 1
	v_cndmask_b32_e32 v1, 0, v241, vcc
	v_or3_b32 v1, v2, v1, v15
	v_or3_b32 v1, v1, v14, v13
	v_or3_b32 v1, v1, v12, v11
	v_or3_b32 v1, v1, v10, v9
	v_or3_b32 v1, v1, v8, v5
	v_or3_b32 v1, v1, v4, v3
	v_or3_b32 v0, v1, v0, v6
	v_or3_b32 v47, v0, v7, v46
	v_lshl_add_u64 v[0:1], s[26:27], 0, v[162:163]
	s_mov_b32 s26, s34
	v_writelane_b32 v254, s26, 58
	global_load_dwordx4 v[24:27], v[0:1], off
	global_load_dwordx4 v[16:19], v[0:1], off offset:1024
	v_writelane_b32 v254, s27, 59
	s_lshl_b64 s[26:27], s[34:35], 12
	s_add_u32 s30, s30, s26
	s_addc_u32 s31, s31, s27
	v_add_co_u32_e32 v0, vcc, s72, v0
	v_lshl_add_u64 v[12:13], s[30:31], 0, v[162:163]
	s_nop 0
	v_addc_co_u32_e32 v1, vcc, 0, v1, vcc
	global_load_dwordx4 v[28:31], v[0:1], off
	global_load_dwordx4 v[20:23], v[0:1], off offset:1024
	s_nop 0
	global_load_dwordx4 v[0:3], v[12:13], off
	global_load_dwordx4 v[4:7], v[12:13], off offset:1024
	global_load_dwordx4 v[8:11], v[12:13], off offset:2048
	s_nop 0
	global_load_dwordx4 v[12:15], v[12:13], off offset:3072
	v_readlane_b32 s30, v252, 48
	s_add_u32 s30, s30, s24
	v_readlane_b32 s31, v252, 50
	s_addc_u32 s31, s31, s25
	v_bfe_i32 v174, v32, 21, 1
	v_bfe_i32 v175, v32, 22, 1
	v_bfe_i32 v176, v32, 23, 1
	v_bfe_i32 v188, v32, 24, 1
	v_bfe_i32 v189, v32, 25, 1
	v_bfe_i32 v190, v32, 26, 1
	v_bfe_i32 v191, v32, 27, 1
	v_bfe_i32 v192, v32, 28, 1
	v_bfe_i32 v193, v32, 29, 1
	v_bfe_i32 v194, v32, 30, 1
	v_ashrrev_i32_e32 v195, 31, v32
	v_and_b32_e32 v32, -16, v34
	v_lshl_add_u64 v[164:165], s[30:31], 0, v[162:163]
	v_readlane_b32 s30, v252, 52
	v_add_u32_e32 v32, s0, v32
	v_lshlrev_b32_e32 v34, 2, v161
	s_add_u32 s30, s30, s26
	v_readlane_b32 s31, v252, 54
	v_sub_u32_e32 v32, v32, v34
	v_readlane_b32 s0, v254, 14
	s_addc_u32 s31, s31, s27
	v_lshl_add_u64 v[166:167], s[30:31], 0, v[162:163]
	v_add_u32_e32 v212, s0, v32
	v_readlane_b32 s0, v254, 16
	s_add_u32 s30, s0, s24
	v_readlane_b32 s0, v254, 18
	s_addc_u32 s31, s0, s25
	v_readlane_b32 s0, v254, 17
	v_bfe_i32 v183, v35, 3, 1
	v_lshl_add_u64 v[152:153], s[30:31], 0, v[162:163]
	s_add_u32 s30, s0, s26
	v_readlane_b32 s0, v254, 19
	v_mov_b32_e32 v34, v33
	v_mov_b32_e32 v35, v33
	v_bfe_i32 v185, v40, 5, 1
	v_bfe_i32 v186, v41, 6, 1
	v_bfe_i32 v187, v42, 7, 1
	v_bfe_i32 v196, v43, 8, 1
	v_bfe_i32 v197, v44, 9, 1
	v_bfe_i32 v198, v44, 10, 1
	v_bfe_i32 v199, v45, 11, 1
	v_bfe_i32 v200, v45, 12, 1
	v_bfe_i32 v201, v46, 13, 1
	v_bfe_i32 v202, v46, 14, 1
	v_bfe_i32 v203, v47, 15, 1
	v_bfe_i32 v204, v47, 24, 1
	v_bfe_i32 v205, v47, 25, 1
	v_bfe_i32 v206, v47, 26, 1
	v_bfe_i32 v207, v47, 27, 1
	v_bfe_i32 v208, v47, 28, 1
	v_bfe_i32 v209, v47, 29, 1
	v_bfe_i32 v210, v47, 30, 1
	v_ashrrev_i32_e32 v211, 31, v47
	s_addc_u32 s31, s0, s27
	v_mov_b32_e32 v32, v33
	v_mov_b64_e32 v[58:59], v[34:35]
	v_mov_b64_e32 v[42:43], v[34:35]
	v_mov_b64_e32 v[46:47], v[34:35]
	v_mov_b64_e32 v[50:51], v[34:35]
	v_mov_b64_e32 v[54:55], v[34:35]
	v_mov_b64_e32 v[98:99], v[34:35]
	v_mov_b64_e32 v[82:83], v[34:35]
	v_mov_b64_e32 v[86:87], v[34:35]
	v_mov_b64_e32 v[90:91], v[34:35]
	v_mov_b64_e32 v[94:95], v[34:35]
	v_mov_b64_e32 v[118:119], v[34:35]
	v_mov_b64_e32 v[102:103], v[34:35]
	v_mov_b64_e32 v[106:107], v[34:35]
	v_mov_b64_e32 v[110:111], v[34:35]
	v_mov_b64_e32 v[114:115], v[34:35]
	v_mov_b64_e32 v[78:79], v[34:35]
	v_mov_b64_e32 v[62:63], v[34:35]
	v_mov_b64_e32 v[66:67], v[34:35]
	v_mov_b64_e32 v[70:71], v[34:35]
	v_mov_b64_e32 v[74:75], v[34:35]
	v_bfe_i32 v177, v37, 1, 1
	v_bfe_i32 v178, v38, 2, 1
	v_bfe_i32 v184, v39, 4, 1
	v_lshl_add_u64 v[154:155], s[30:31], 0, v[162:163]
	s_mov_b64 s[34:35], 0
	v_readlane_b32 s30, v254, 13
	v_mov_b64_e32 v[56:57], v[32:33]
	v_mov_b64_e32 v[40:41], v[32:33]
	v_mov_b64_e32 v[44:45], v[32:33]
	v_mov_b64_e32 v[48:49], v[32:33]
	v_mov_b64_e32 v[52:53], v[32:33]
	v_mov_b64_e32 v[96:97], v[32:33]
	v_mov_b64_e32 v[80:81], v[32:33]
	v_mov_b64_e32 v[84:85], v[32:33]
	v_mov_b64_e32 v[88:89], v[32:33]
	v_mov_b64_e32 v[92:93], v[32:33]
	v_mov_b64_e32 v[116:117], v[32:33]
	v_mov_b64_e32 v[100:101], v[32:33]
	v_mov_b64_e32 v[104:105], v[32:33]
	v_mov_b64_e32 v[108:109], v[32:33]
	v_mov_b64_e32 v[112:113], v[32:33]
	v_mov_b64_e32 v[76:77], v[32:33]
	v_mov_b64_e32 v[60:61], v[32:33]
	v_mov_b64_e32 v[64:65], v[32:33]
	v_mov_b64_e32 v[68:69], v[32:33]
	v_mov_b64_e32 v[72:73], v[32:33]
	s_branch .LBB0_349
